# natten item prologue: rpb table loads issued without waiting, scale+LDS write deferred past the Q/tile load issue (2 fewer serial round trips per item)
# speedup vs baseline: 1.0019x; 1.0019x over previous
.LBB0_334:
	s_and_b64 vcc, exec, s[0:1]
	s_cbranch_vccz .LBB0_321
	v_writelane_b32 v253, s3, 44
	s_bfe_u32 s0, s2, 0x10006
	s_and_b32 s3, s2, 7
	s_lshl_b32 s0, s0, 3
	s_or_b32 s0, s0, s3
	v_writelane_b32 v253, s0, 45
	s_bfe_u32 s0, s2, 0x30003
	v_mov_b32_e32 v2, v193
	s_lshl_b32 s0, s0, 2
	v_sub_u32_e64 v0, s0, 1 clamp
	v_ashrrev_i32_e32 v6, 6, v2
	v_writelane_b32 v253, s2, 46
	v_add_u32_e32 v7, s0, v6
	s_max_u32 s2, s0, 4
	v_readfirstlane_b32 s0, v0
	s_min_u32 s3, s0, 24
	s_movk_i32 s0, 0x1d1
	v_cmp_gt_i32_e32 vcc, s0, v2
	s_barrier
	v_readlane_b32 s6, v253, 43
	v_readlane_b32 s7, v253, 45
	v_readlane_b32 s8, v255, 34
	s_or_b32 s6, s7, s6
	s_mulk_i32 s6, 0x744
	v_readlane_b32 s18, v253, 22
	v_readlane_b32 s19, v253, 23
	v_lshlrev_b32_e32 v186, 2, v2
	s_add_u32 s6, s18, s6
	s_addc_u32 s7, s19, 0
	s_movk_i32 s4, 0xd1
	v_cmp_gt_u32_e32 vcc, s4, v2
	global_load_dword v184, v186, s[6:7]
	v_add_u32_e32 v187, s8, v186
	s_and_saveexec_b64 s[4:5], vcc
	global_load_dword v185, v186, s[6:7] offset:1024
	s_mov_b64 exec, s[4:5]
.LBB0_343:
	v_readlane_b32 s0, v253, 46
	s_ashr_i32 s0, s0, 7
	v_and_b32_e32 v3, 31, v2
	v_bfe_u32 v2, v2, 5, 1
	s_mov_b32 s90, s0
	s_lshl_b32 s0, s0, 4
	v_readlane_b32 s1, v253, 45
	v_lshl_or_b32 v190, v7, 6, v3
	v_lshl_or_b32 v0, v6, 5, v3
	s_or_b32 s4, s0, s1
	v_mul_lo_u32 v4, v0, s91
	v_lshlrev_b32_e32 v0, 4, v2
	v_ashrrev_i32_e32 v191, 31, v190
	v_add3_u32 v192, 0, v4, v0
	v_mad_i64_i32 v[4:5], s[0:1], s4, v198, v[190:191]
	v_readlane_b32 s0, v254, 3
	v_lshlrev_b64 v[4:5], 7, v[4:5]
	v_readlane_b32 s1, v254, 4
	s_add_i32 s96, s2, -4
	s_sub_i32 s2, s3, s2
	v_lshl_add_u64 v[4:5], s[0:1], 0, v[4:5]
	v_lshl_add_u64 v[4:5], v[4:5], 0, v[0:1]
	s_mov_b64 s[0:1], 0x1000
	v_lshl_add_u64 v[12:13], v[4:5], 0, s[0:1]
	s_movk_i32 s0, 0x1000
	v_add_co_u32_e32 v8, vcc, s0, v4
	global_load_dwordx4 v[130:133], v[4:5], off
	s_nop 0
	v_addc_co_u32_e32 v9, vcc, 0, v5, vcc
	global_load_dwordx4 v[158:161], v[8:9], off
	s_add_i32 s97, s2, 11
	s_mul_hi_i32 s0, s4, 0x48000
	s_mul_i32 s4, s4, 0x48000
	v_readlane_b32 s6, v254, 40
	v_readlane_b32 s7, v254, 41
	s_add_u32 s92, s6, s4
	s_addc_u32 s93, s7, s0
	v_readlane_b32 s1, v254, 1
	s_add_u32 s94, s1, s4
	v_readlane_b32 s1, v254, 2
	v_readlane_b32 s6, v255, 40
	s_addc_u32 s95, s1, s0
	v_readlane_b32 s7, v255, 41
	s_lshl_b32 s6, s96, 6
	s_lshl_b64 s[0:1], s[6:7], 7
	s_add_u32 s4, s92, s0
	s_addc_u32 s5, s93, s1
	s_lshl_b32 s0, s96, 7
	s_add_u32 s0, s94, s0
	s_addc_u32 s1, s95, 0
	s_movk_i32 s3, 0x1200
	v_lshlrev_b32_e32 v191, 2, v2
	global_load_dwordx4 v[134:137], v[4:5], off offset:32
	global_load_dwordx4 v[146:149], v[12:13], off offset:32
	global_load_dwordx4 v[138:141], v[4:5], off offset:64
	global_load_dwordx4 v[150:153], v[12:13], off offset:64
	global_load_dwordx4 v[142:145], v[4:5], off offset:96
	global_load_dwordx4 v[154:157], v[12:13], off offset:96
	v_mov_b32_e32 v4, v193
	s_nop 0
	v_ashrrev_i32_e32 v5, 31, v4
	v_lshl_add_u64 v[8:9], v[4:5], 4, s[4:5]
	global_load_dwordx4 v[8:11], v[8:9], off
	v_add_u32_e32 v20, 0x100, v4
	v_ashrrev_i32_e32 v21, 31, v20
	v_lshl_add_u64 v[12:13], v[20:21], 4, s[4:5]
	global_load_dwordx4 v[12:15], v[12:13], off
	v_lshlrev_b32_e32 v0, 4, v4
	v_and_b32_e32 v0, 0x70, v0
	v_lshl_add_u64 v[22:23], s[0:1], 0, v[0:1]
	v_ashrrev_i32_e32 v0, 3, v4
	v_mad_i64_i32 v[4:5], s[0:1], v0, s3, v[22:23]
	global_load_dwordx4 v[16:19], v[4:5], off
	v_ashrrev_i32_e32 v0, 3, v20
	v_mad_i64_i32 v[4:5], s[0:1], v0, s3, v[22:23]
	global_load_dwordx4 v[20:23], v[4:5], off
	v_mov_b32_e32 v4, v193
	s_nop 0
	v_ashrrev_i32_e32 v0, 31, v4
	v_lshrrev_b32_e32 v0, 29, v0
	v_add_u32_e32 v0, v4, v0
	v_lshrrev_b32_e32 v5, 3, v0
	v_and_b32_e32 v0, 0xffffff8, v0
	v_sub_u32_e32 v0, v4, v0
	v_mul_lo_u32 v5, v5, s91
	v_lshlrev_b32_e32 v0, 4, v0
	v_add3_u32 v0, 0, v5, v0
	s_waitcnt vmcnt(12)
	v_mul_f32_e32 v184, 0x3fb8aa3b, v184
	v_cmp_gt_u32_e32 vcc, 0xd1, v193
	ds_write_b32 v187, v184
	s_and_saveexec_b64 s[0:1], vcc
	v_mul_f32_e32 v185, 0x3fb8aa3b, v185
	ds_write_b32 v187, v185 offset:1024
	s_mov_b64 exec, s[0:1]
	s_waitcnt vmcnt(3)
	ds_write_b128 v192, v[158:161] offset:47104
	ds_write_b128 v192, v[146:149] offset:47136
	ds_write_b128 v192, v[150:153] offset:47168
	ds_write_b128 v192, v[154:157] offset:47200
	ds_write_b128 v0, v[8:11]
	v_add_u32_e32 v8, 0x100, v4
	v_ashrrev_i32_e32 v0, 31, v8
	v_lshrrev_b32_e32 v0, 29, v0
	v_add_u32_e32 v0, v8, v0
	v_lshrrev_b32_e32 v5, 3, v0
	v_and_b32_e32 v0, 0xffffff8, v0
	v_sub_u32_e32 v0, v8, v0
	v_mul_lo_u32 v5, v5, s91
	v_lshlrev_b32_e32 v0, 4, v0
	v_add3_u32 v0, 0, v5, v0
	s_waitcnt vmcnt(2)
	ds_write_b128 v0, v[12:15]
	v_lshlrev_b32_e32 v0, 4, v4
	v_and_b32_e32 v0, 0x70, v0
	v_add_u32_e32 v0, 0, v0
	v_lshrrev_b32_e32 v4, 3, v4
	v_mad_u64_u32 v[4:5], s[0:1], v4, s91, v[0:1]
	s_waitcnt vmcnt(1)
	ds_write_b128 v4, v[16:19] offset:13312
	v_lshrrev_b32_e32 v4, 3, v8
	v_mad_u64_u32 v[4:5], s[0:1], v4, s91, v[0:1]
	s_lshl_b32 s1, s97, 6
	s_or_b32 s0, s6, 64
	s_sub_i32 s1, 0x800, s1
	s_cmp_gt_i32 s2, -11
	s_cselect_b32 s6, s0, s1
	s_lshl_b64 s[0:1], s[6:7], 7
	s_waitcnt vmcnt(0)
	ds_write_b128 v4, v[20:23] offset:13312
	s_add_u32 s4, s92, s0
	v_mov_b32_e32 v4, v193
	s_addc_u32 s5, s93, s1
	s_mov_b32 s1, s7
	v_writelane_b32 v255, s0, 40
	v_ashrrev_i32_e32 v5, 31, v4
	v_lshl_add_u64 v[8:9], v[4:5], 4, s[4:5]
	v_writelane_b32 v255, s1, 41
	s_lshl_b64 s[0:1], s[6:7], 1
	global_load_dwordx4 v[146:149], v[8:9], off
	v_add_u32_e32 v8, 0x100, v4
	s_add_u32 s0, s94, s0
	v_ashrrev_i32_e32 v9, 31, v8
	v_lshlrev_b32_e32 v0, 4, v4
	s_addc_u32 s1, s95, s1
	v_lshl_add_u64 v[10:11], v[8:9], 4, s[4:5]
	v_and_b32_e32 v0, 0x70, v0
	global_load_dwordx4 v[150:153], v[10:11], off
	v_lshl_add_u64 v[10:11], s[0:1], 0, v[0:1]
	v_ashrrev_i32_e32 v0, 3, v4
	v_mad_i64_i32 v[4:5], s[0:1], v0, s3, v[10:11]
	v_ashrrev_i32_e32 v0, 3, v8
	global_load_dwordx4 v[154:157], v[4:5], off
	v_mad_i64_i32 v[4:5], s[0:1], v0, s3, v[10:11]
	global_load_dwordx4 v[158:161], v[4:5], off
	s_mov_b64 s[0:1], -1
	s_cmp_gt_i32 s2, -16
	s_waitcnt lgkmcnt(0)
	s_barrier
	s_cbranch_scc1 .LBB0_345
	v_lshlrev_b32_e32 v66, 2, v2
	s_mov_b64 s[0:1], 0
